# x->bf16 conversion loops inside the GEMM1 phase software-pipelined (next trip's loads issued before the current reduction)
# speedup vs baseline: 1.0250x; 1.0001x over previous
.LBB0_109:
	v_writelane_b32 v255, s52, 1
	s_nop 1
	v_writelane_b32 v255, s53, 2
	v_writelane_b32 v255, s54, 3
	v_writelane_b32 v255, s55, 4
	v_writelane_b32 v255, s56, 5
	v_writelane_b32 v255, s57, 6
	v_writelane_b32 v255, s58, 7
	v_writelane_b32 v255, s59, 8
	v_writelane_b32 v255, s60, 9
	v_writelane_b32 v255, s61, 10
	v_writelane_b32 v255, s62, 11
	v_writelane_b32 v255, s63, 12
	v_writelane_b32 v255, s64, 13
	v_writelane_b32 v255, s65, 14
	v_writelane_b32 v255, s66, 15
	v_writelane_b32 v255, s67, 16
	s_or_b64 exec, exec, s[0:1]
	v_readfirstlane_b32 s67, v0
	s_lshr_b32 s20, s67, 6
	s_and_b32 s0, s86, 1
	s_cmp_eq_u32 s0, 0
	s_cselect_b64 s[90:91], -1, 0
	s_cmp_eq_u32 s0, 1
	v_writelane_b32 v255, s0, 17
	s_cselect_b64 s[0:1], -1, 0
	v_writelane_b32 v255, s0, 19
	s_cmpk_gt_u32 s67, 0x1fff
	s_waitcnt lgkmcnt(0)
	v_writelane_b32 v255, s1, 20
	s_cselect_b64 s[0:1], -1, 0
	s_or_b64 s[0:1], s[90:91], s[0:1]
	s_and_b64 vcc, exec, s[0:1]
	s_barrier
	s_cbranch_vccnz .LBB0_112
	s_lshl_b32 s0, s86, 7
	s_add_i32 s6, s20, s0
	s_add_i32 s2, s0, 0x8070
	s_add_i32 s0, s6, 0x8008
	v_mbcnt_lo_u32_b32 v1, -1, 0
	s_ashr_i32 s1, s0, 31
	v_mbcnt_hi_u32_b32 v2, -1, v1
	s_add_i32 s3, s6, 0x7ff0
	s_lshl_b64 s[4:5], s[0:1], 11
	v_and_b32_e32 v1, 64, v2
	s_add_u32 s4, s80, s4
	v_add_u32_e32 v7, 64, v1
	v_xor_b32_e32 v1, 1, v2
	s_addc_u32 s5, s81, s5
	s_add_i32 s10, s6, 0x8000
	v_cmp_lt_i32_e32 vcc, v1, v7
	v_xor_b32_e32 v3, 2, v2
	s_ashr_i32 s11, s10, 31
	v_cndmask_b32_e32 v1, v2, v1, vcc
	v_cmp_lt_i32_e32 vcc, v3, v7
	v_xor_b32_e32 v4, 4, v2
	s_lshl_b64 s[6:7], s[10:11], 12
	v_readlane_b32 s36, v255, 1
	v_cndmask_b32_e32 v3, v2, v3, vcc
	v_cmp_lt_i32_e32 vcc, v4, v7
	v_xor_b32_e32 v5, 8, v2
	v_readlane_b32 s37, v255, 2
	s_add_u32 s6, s36, s6
	v_cndmask_b32_e32 v4, v2, v4, vcc
	v_cmp_lt_i32_e32 vcc, v5, v7
	v_xor_b32_e32 v6, 16, v2
	s_addc_u32 s7, s37, s7
	s_lshl_b64 s[0:1], s[0:1], 12
	v_cndmask_b32_e32 v5, v2, v5, vcc
	v_cmp_lt_i32_e32 vcc, v6, v7
	v_xor_b32_e32 v8, 32, v2
	s_add_u32 s8, s36, s0
	v_cndmask_b32_e32 v6, v2, v6, vcc
	v_cmp_lt_i32_e32 vcc, v8, v7
	s_addc_u32 s9, s37, s1
	s_lshl_b64 s[0:1], s[10:11], 11
	v_cndmask_b32_e32 v2, v2, v8, vcc
	v_mov_b32_e32 v147, 0
	s_add_u32 s10, s80, s0
	v_lshlrev_b32_e32 v1, 2, v1
	v_lshlrev_b32_e32 v3, 2, v3
	v_lshlrev_b32_e32 v4, 2, v4
	v_lshlrev_b32_e32 v5, 2, v5
	v_lshlrev_b32_e32 v6, 2, v6
	v_lshlrev_b32_e32 v7, 2, v2
	v_mov_b32_e32 v149, v147
	s_addc_u32 s11, s81, s1
	s_mov_b32 s14, 0x3a800000
	v_mov_b32_e32 v2, 0x358637bd
	s_mov_b32 s15, 0x800000
	v_readlane_b32 s38, v255, 3
	v_readlane_b32 s39, v255, 4
	v_readlane_b32 s40, v255, 5
	v_readlane_b32 s41, v255, 6
	v_readlane_b32 s42, v255, 7
	v_readlane_b32 s43, v255, 8
	v_readlane_b32 s44, v255, 9
	v_readlane_b32 s45, v255, 10
	v_readlane_b32 s46, v255, 11
	v_readlane_b32 s47, v255, 12
	v_readlane_b32 s48, v255, 13
	v_readlane_b32 s49, v255, 14
	v_readlane_b32 s50, v255, 15
	v_readlane_b32 s51, v255, 16
	v_lshl_add_u64 v[112:113], s[6:7], 0, v[148:149]
	v_lshl_add_u64 v[114:115], s[8:9], 0, v[148:149]
	global_load_dwordx4 v[80:83], v[112:113], off nt
	global_load_dwordx4 v[84:87], v[112:113], off offset:1024 nt
	global_load_dwordx4 v[88:91], v[114:115], off nt
	global_load_dwordx4 v[92:95], v[114:115], off offset:1024 nt
	global_load_dwordx4 v[96:99], v[112:113], off offset:2048 nt
	global_load_dwordx4 v[100:103], v[112:113], off offset:3072 nt
	global_load_dwordx4 v[104:107], v[114:115], off offset:2048 nt
	global_load_dwordx4 v[108:111], v[114:115], off offset:3072 nt
	s_waitcnt vmcnt(0)
.LBB0_111:
	s_waitcnt vmcnt(8)
	v_mov_b32_e32 v8, v80
	v_mov_b32_e32 v9, v81
	v_mov_b32_e32 v10, v82
	v_mov_b32_e32 v11, v83
	v_mov_b32_e32 v12, v84
	v_mov_b32_e32 v13, v85
	v_mov_b32_e32 v14, v86
	v_mov_b32_e32 v15, v87
	v_mov_b32_e32 v16, v88
	v_mov_b32_e32 v17, v89
	v_mov_b32_e32 v18, v90
	v_mov_b32_e32 v19, v91
	v_mov_b32_e32 v20, v92
	v_mov_b32_e32 v21, v93
	v_mov_b32_e32 v22, v94
	v_mov_b32_e32 v23, v95
	v_mov_b32_e32 v24, v96
	v_mov_b32_e32 v25, v97
	v_mov_b32_e32 v26, v98
	v_mov_b32_e32 v27, v99
	v_mov_b32_e32 v28, v100
	v_mov_b32_e32 v29, v101
	v_mov_b32_e32 v30, v102
	v_mov_b32_e32 v31, v103
	v_mov_b32_e32 v32, v104
	v_mov_b32_e32 v33, v105
	v_mov_b32_e32 v34, v106
	v_mov_b32_e32 v35, v107
	v_mov_b32_e32 v36, v108
	v_mov_b32_e32 v37, v109
	v_mov_b32_e32 v38, v110
	v_mov_b32_e32 v39, v111
	s_add_i32 s3, s3, 16
	v_lshl_add_u64 v[42:43], s[4:5], 0, v[146:147]
	s_add_u32 s4, s4, 0x8000
	s_addc_u32 s5, s5, 0
	s_add_u32 s6, s6, 0x10000
	s_addc_u32 s7, s7, 0
	s_add_u32 s8, s8, 0x10000
	s_addc_u32 s9, s9, 0
	v_lshl_add_u64 v[40:41], s[10:11], 0, v[146:147]
	s_add_u32 s10, s10, 0x8000
	s_addc_u32 s11, s11, 0
	s_cmp_lt_i32 s3, s2
	s_cbranch_scc0 .Lmy_xpa_skip
	v_lshl_add_u64 v[112:113], s[6:7], 0, v[148:149]
	v_lshl_add_u64 v[114:115], s[8:9], 0, v[148:149]
	global_load_dwordx4 v[80:83], v[112:113], off nt
	global_load_dwordx4 v[84:87], v[112:113], off offset:1024 nt
	global_load_dwordx4 v[88:91], v[114:115], off nt
	global_load_dwordx4 v[92:95], v[114:115], off offset:1024 nt
	global_load_dwordx4 v[96:99], v[112:113], off offset:2048 nt
	global_load_dwordx4 v[100:103], v[112:113], off offset:3072 nt
	global_load_dwordx4 v[104:107], v[114:115], off offset:2048 nt
	global_load_dwordx4 v[108:111], v[114:115], off offset:3072 nt
.Lmy_xpa_skip:
	v_mov_b32_e32 v46, v9
	v_mov_b32_e32 v47, v13
	v_mov_b32_e32 v54, v17
	v_mov_b32_e32 v55, v21
	v_mov_b32_e32 v44, v8
	v_mov_b32_e32 v45, v12
	v_mov_b32_e32 v52, v16
	v_mov_b32_e32 v53, v20
	v_mov_b32_e32 v62, v25
	v_mov_b32_e32 v63, v29
	v_mov_b32_e32 v68, v33
	v_mov_b32_e32 v69, v37
	v_pk_mul_f32 v[46:47], v[46:47], v[46:47]
	v_pk_mul_f32 v[54:55], v[54:55], v[54:55]
	v_mov_b32_e32 v48, v10
	v_mov_b32_e32 v49, v14
	v_mov_b32_e32 v56, v18
	v_mov_b32_e32 v57, v22
	v_mov_b32_e32 v60, v24
	v_mov_b32_e32 v61, v28
	v_mov_b32_e32 v66, v32
	v_mov_b32_e32 v67, v36
	v_pk_mul_f32 v[62:63], v[62:63], v[62:63]
	v_pk_mul_f32 v[68:69], v[68:69], v[68:69]
	v_pk_fma_f32 v[44:45], v[44:45], v[44:45], v[46:47]
	v_pk_fma_f32 v[46:47], v[52:53], v[52:53], v[54:55]
	v_mov_b32_e32 v50, v11
	v_mov_b32_e32 v51, v15
	v_mov_b32_e32 v58, v19
	v_mov_b32_e32 v59, v23
	v_mov_b32_e32 v64, v26
	v_mov_b32_e32 v65, v30
	v_mov_b32_e32 v72, v34
	v_mov_b32_e32 v73, v38
	v_pk_fma_f32 v[52:53], v[60:61], v[60:61], v[62:63]
	v_pk_fma_f32 v[54:55], v[66:67], v[66:67], v[68:69]
	v_pk_fma_f32 v[44:45], v[48:49], v[48:49], v[44:45]
	v_pk_fma_f32 v[46:47], v[56:57], v[56:57], v[46:47]
	v_mov_b32_e32 v70, v27
	v_mov_b32_e32 v71, v31
	v_mov_b32_e32 v74, v35
	v_mov_b32_e32 v75, v39
	v_pk_fma_f32 v[48:49], v[64:65], v[64:65], v[52:53]
	v_pk_fma_f32 v[52:53], v[72:73], v[72:73], v[54:55]
	v_pk_fma_f32 v[44:45], v[50:51], v[50:51], v[44:45]
	v_pk_fma_f32 v[46:47], v[58:59], v[58:59], v[46:47]
	v_pk_fma_f32 v[48:49], v[70:71], v[70:71], v[48:49]
	v_pk_fma_f32 v[50:51], v[74:75], v[74:75], v[52:53]
	v_mov_b32_e32 v52, v46
	v_mov_b32_e32 v53, v44
	v_mov_b32_e32 v44, v47
	v_mov_b32_e32 v46, v50
	v_mov_b32_e32 v47, v48
	v_pk_add_f32 v[44:45], v[52:53], v[44:45]
	v_mov_b32_e32 v48, v51
	v_pk_add_f32 v[44:45], v[44:45], v[46:47]
	s_nop 0
	v_pk_add_f32 v[44:45], v[44:45], v[48:49]
	ds_bpermute_b32 v47, v1, v45
	ds_bpermute_b32 v46, v1, v44
	s_waitcnt lgkmcnt(0)
	v_pk_add_f32 v[44:45], v[44:45], v[46:47]
	ds_bpermute_b32 v47, v3, v45
	ds_bpermute_b32 v46, v3, v44
	s_waitcnt lgkmcnt(0)
	v_pk_add_f32 v[44:45], v[44:45], v[46:47]
	ds_bpermute_b32 v47, v4, v45
	ds_bpermute_b32 v46, v4, v44
	s_waitcnt lgkmcnt(0)
	v_pk_add_f32 v[44:45], v[44:45], v[46:47]
	ds_bpermute_b32 v47, v5, v45
	ds_bpermute_b32 v46, v5, v44
	s_waitcnt lgkmcnt(0)
	v_pk_add_f32 v[44:45], v[44:45], v[46:47]
	ds_bpermute_b32 v47, v6, v45
	ds_bpermute_b32 v46, v6, v44
	s_waitcnt lgkmcnt(0)
	v_pk_add_f32 v[44:45], v[44:45], v[46:47]
	ds_bpermute_b32 v47, v7, v45
	ds_bpermute_b32 v46, v7, v44
	s_waitcnt lgkmcnt(0)
	v_pk_add_f32 v[44:45], v[44:45], v[46:47]
	s_nop 0
	v_pk_fma_f32 v[44:45], v[44:45], s[14:15], v[2:3] op_sel_hi:[1,0,0]
	s_nop 0
	v_mul_f32_e32 v46, 0x4b800000, v45
	v_cmp_gt_f32_e64 s[0:1], s15, v45
	v_mul_f32_e32 v47, 0x4b800000, v44
	v_cmp_gt_f32_e32 vcc, s15, v44
	v_cndmask_b32_e64 v45, v45, v46, s[0:1]
	v_rsq_f32_e32 v45, v45
	v_cndmask_b32_e32 v44, v44, v47, vcc
	v_rsq_f32_e32 v46, v44
	v_mul_f32_e32 v44, 0x45800000, v45
	v_cndmask_b32_e64 v44, v45, v44, s[0:1]
	v_mul_f32_e32 v47, 0x45800000, v46
	v_cndmask_b32_e32 v46, v46, v47, vcc
	v_pk_mul_f32 v[8:9], v[8:9], v[44:45] op_sel_hi:[1,0]
	v_pk_mul_f32 v[10:11], v[10:11], v[44:45] op_sel_hi:[1,0]
	v_pk_mul_f32 v[16:17], v[16:17], v[46:47] op_sel_hi:[1,0]
	v_pk_mul_f32 v[18:19], v[18:19], v[46:47] op_sel_hi:[1,0]
	v_pk_mul_f32 v[12:13], v[12:13], v[44:45] op_sel_hi:[1,0]
	v_pk_mul_f32 v[14:15], v[14:15], v[44:45] op_sel_hi:[1,0]
	v_pk_mul_f32 v[20:21], v[20:21], v[46:47] op_sel_hi:[1,0]
	v_pk_mul_f32 v[22:23], v[22:23], v[46:47] op_sel_hi:[1,0]
	v_pk_mul_f32 v[24:25], v[24:25], v[44:45] op_sel_hi:[1,0]
	v_pk_mul_f32 v[26:27], v[26:27], v[44:45] op_sel_hi:[1,0]
	v_pk_mul_f32 v[32:33], v[32:33], v[46:47] op_sel_hi:[1,0]
	v_pk_mul_f32 v[34:35], v[34:35], v[46:47] op_sel_hi:[1,0]
	v_pk_mul_f32 v[28:29], v[28:29], v[44:45] op_sel_hi:[1,0]
	v_pk_mul_f32 v[30:31], v[30:31], v[44:45] op_sel_hi:[1,0]
	v_pk_mul_f32 v[36:37], v[36:37], v[46:47] op_sel_hi:[1,0]
	v_pk_mul_f32 v[38:39], v[38:39], v[46:47] op_sel_hi:[1,0]
	v_cvt_pk_bf16_f32 v8, v8, v9
	v_cvt_pk_bf16_f32 v9, v10, v11
	v_cvt_pk_bf16_f32 v10, v16, v17
	v_cvt_pk_bf16_f32 v11, v18, v19
	v_cvt_pk_bf16_f32 v12, v12, v13
	v_cvt_pk_bf16_f32 v13, v14, v15
	v_cvt_pk_bf16_f32 v14, v20, v21
	v_cvt_pk_bf16_f32 v15, v22, v23
	v_cvt_pk_bf16_f32 v16, v24, v25
	v_cvt_pk_bf16_f32 v17, v26, v27
	v_cvt_pk_bf16_f32 v18, v32, v33
	v_cvt_pk_bf16_f32 v19, v34, v35
	v_cvt_pk_bf16_f32 v20, v28, v29
	v_cvt_pk_bf16_f32 v21, v30, v31
	v_cvt_pk_bf16_f32 v22, v36, v37
	v_cvt_pk_bf16_f32 v23, v38, v39
	global_store_dwordx2 v[40:41], v[8:9], off
	global_store_dwordx2 v[42:43], v[10:11], off
	global_store_dwordx2 v[40:41], v[12:13], off offset:512
	global_store_dwordx2 v[42:43], v[14:15], off offset:512
	global_store_dwordx2 v[40:41], v[16:17], off offset:1024
	global_store_dwordx2 v[42:43], v[18:19], off offset:1024
	global_store_dwordx2 v[40:41], v[20:21], off offset:1536
	global_store_dwordx2 v[42:43], v[22:23], off offset:1536
	s_cbranch_scc1 .LBB0_111

.LBB0_187:
	s_cmpk_lt_u32 s67, 0x2000
	s_cselect_b64 s[0:1], -1, 0
	s_and_b64 s[0:1], s[90:91], s[0:1]
	v_readlane_b32 s36, v255, 1
	s_andn2_b64 vcc, exec, s[0:1]
	v_readlane_b32 s37, v255, 2
	v_readlane_b32 s38, v255, 3
	v_readlane_b32 s39, v255, 4
	v_readlane_b32 s40, v255, 5
	v_readlane_b32 s41, v255, 6
	v_readlane_b32 s42, v255, 7
	v_readlane_b32 s43, v255, 8
	v_readlane_b32 s44, v255, 9
	v_readlane_b32 s45, v255, 10
	v_readlane_b32 s46, v255, 11
	v_readlane_b32 s47, v255, 12
	v_readlane_b32 s48, v255, 13
	v_readlane_b32 s49, v255, 14
	v_readlane_b32 s50, v255, 15
	v_readlane_b32 s51, v255, 16
	s_cbranch_vccnz .LBB0_190
	s_lshl_b32 s0, s86, 7
	s_add_i32 s8, s20, s0
	s_add_i32 s2, s0, 0x8070
	s_add_i32 s0, s8, 0x8008
	v_mbcnt_lo_u32_b32 v1, -1, 0
	s_ashr_i32 s1, s0, 31
	v_mbcnt_hi_u32_b32 v2, -1, v1
	s_add_i32 s3, s8, 0x7ff0
	s_lshl_b64 s[4:5], s[0:1], 11
	v_and_b32_e32 v1, 64, v2
	s_add_u32 s6, s80, s4
	v_add_u32_e32 v7, 64, v1
	v_xor_b32_e32 v1, 1, v2
	s_addc_u32 s7, s81, s5
	s_add_i32 s4, s8, 0x8000
	v_cmp_lt_i32_e32 vcc, v1, v7
	v_xor_b32_e32 v3, 2, v2
	s_ashr_i32 s5, s4, 31
	v_cndmask_b32_e32 v1, v2, v1, vcc
	v_cmp_lt_i32_e32 vcc, v3, v7
	v_xor_b32_e32 v4, 4, v2
	s_lshl_b64 s[8:9], s[4:5], 12
	v_cndmask_b32_e32 v3, v2, v3, vcc
	v_cmp_lt_i32_e32 vcc, v4, v7
	v_xor_b32_e32 v5, 8, v2
	s_add_u32 s8, s36, s8
	v_cndmask_b32_e32 v4, v2, v4, vcc
	v_cmp_lt_i32_e32 vcc, v5, v7
	v_xor_b32_e32 v6, 16, v2
	s_addc_u32 s9, s37, s9
	s_lshl_b64 s[0:1], s[0:1], 12
	v_cndmask_b32_e32 v5, v2, v5, vcc
	v_cmp_lt_i32_e32 vcc, v6, v7
	v_xor_b32_e32 v8, 32, v2
	s_add_u32 s10, s36, s0
	v_cndmask_b32_e32 v6, v2, v6, vcc
	v_cmp_lt_i32_e32 vcc, v8, v7
	s_addc_u32 s11, s37, s1
	s_lshl_b64 s[0:1], s[4:5], 11
	v_cndmask_b32_e32 v2, v2, v8, vcc
	v_mov_b32_e32 v147, 0
	s_add_u32 s14, s80, s0
	v_lshlrev_b32_e32 v1, 2, v1
	v_lshlrev_b32_e32 v3, 2, v3
	v_lshlrev_b32_e32 v4, 2, v4
	v_lshlrev_b32_e32 v5, 2, v5
	v_lshlrev_b32_e32 v6, 2, v6
	v_lshlrev_b32_e32 v7, 2, v2
	v_mov_b32_e32 v149, v147
	s_addc_u32 s15, s81, s1
	s_mov_b32 s18, 0x3a800000
	v_mov_b32_e32 v2, 0x358637bd
	s_mov_b32 s4, 0x800000
	v_lshl_add_u64 v[112:113], s[8:9], 0, v[148:149]
	v_lshl_add_u64 v[114:115], s[10:11], 0, v[148:149]
	global_load_dwordx4 v[80:83], v[112:113], off nt
	global_load_dwordx4 v[84:87], v[112:113], off offset:1024 nt
	global_load_dwordx4 v[88:91], v[114:115], off nt
	global_load_dwordx4 v[92:95], v[114:115], off offset:1024 nt
	global_load_dwordx4 v[96:99], v[112:113], off offset:2048 nt
	global_load_dwordx4 v[100:103], v[112:113], off offset:3072 nt
	global_load_dwordx4 v[104:107], v[114:115], off offset:2048 nt
	global_load_dwordx4 v[108:111], v[114:115], off offset:3072 nt
	s_waitcnt vmcnt(0)
.LBB0_189:
	s_waitcnt vmcnt(8)
	v_mov_b32_e32 v8, v80
	v_mov_b32_e32 v9, v81
	v_mov_b32_e32 v10, v82
	v_mov_b32_e32 v11, v83
	v_mov_b32_e32 v12, v84
	v_mov_b32_e32 v13, v85
	v_mov_b32_e32 v14, v86
	v_mov_b32_e32 v15, v87
	v_mov_b32_e32 v16, v88
	v_mov_b32_e32 v17, v89
	v_mov_b32_e32 v18, v90
	v_mov_b32_e32 v19, v91
	v_mov_b32_e32 v20, v92
	v_mov_b32_e32 v21, v93
	v_mov_b32_e32 v22, v94
	v_mov_b32_e32 v23, v95
	v_mov_b32_e32 v24, v96
	v_mov_b32_e32 v25, v97
	v_mov_b32_e32 v26, v98
	v_mov_b32_e32 v27, v99
	v_mov_b32_e32 v28, v100
	v_mov_b32_e32 v29, v101
	v_mov_b32_e32 v30, v102
	v_mov_b32_e32 v31, v103
	v_mov_b32_e32 v32, v104
	v_mov_b32_e32 v33, v105
	v_mov_b32_e32 v34, v106
	v_mov_b32_e32 v35, v107
	v_mov_b32_e32 v36, v108
	v_mov_b32_e32 v37, v109
	v_mov_b32_e32 v38, v110
	v_mov_b32_e32 v39, v111
	s_add_i32 s3, s3, 16
	v_lshl_add_u64 v[42:43], s[6:7], 0, v[146:147]
	s_add_u32 s6, s6, 0x8000
	s_addc_u32 s7, s7, 0
	s_add_u32 s8, s8, 0x10000
	s_addc_u32 s9, s9, 0
	s_add_u32 s10, s10, 0x10000
	s_addc_u32 s11, s11, 0
	v_lshl_add_u64 v[40:41], s[14:15], 0, v[146:147]
	s_add_u32 s14, s14, 0x8000
	s_addc_u32 s15, s15, 0
	s_cmp_lt_i32 s3, s2
	s_cbranch_scc0 .Lmy_xpb_skip
	v_lshl_add_u64 v[112:113], s[8:9], 0, v[148:149]
	v_lshl_add_u64 v[114:115], s[10:11], 0, v[148:149]
	global_load_dwordx4 v[80:83], v[112:113], off nt
	global_load_dwordx4 v[84:87], v[112:113], off offset:1024 nt
	global_load_dwordx4 v[88:91], v[114:115], off nt
	global_load_dwordx4 v[92:95], v[114:115], off offset:1024 nt
	global_load_dwordx4 v[96:99], v[112:113], off offset:2048 nt
	global_load_dwordx4 v[100:103], v[112:113], off offset:3072 nt
	global_load_dwordx4 v[104:107], v[114:115], off offset:2048 nt
	global_load_dwordx4 v[108:111], v[114:115], off offset:3072 nt
.Lmy_xpb_skip:
	v_mov_b32_e32 v46, v9
	v_mov_b32_e32 v47, v13
	v_mov_b32_e32 v54, v17
	v_mov_b32_e32 v55, v21
	v_mov_b32_e32 v44, v8
	v_mov_b32_e32 v45, v12
	v_mov_b32_e32 v52, v16
	v_mov_b32_e32 v53, v20
	v_mov_b32_e32 v62, v25
	v_mov_b32_e32 v63, v29
	v_mov_b32_e32 v70, v33
	v_mov_b32_e32 v71, v37
	v_pk_mul_f32 v[46:47], v[46:47], v[46:47]
	v_pk_mul_f32 v[54:55], v[54:55], v[54:55]
	v_mov_b32_e32 v48, v10
	v_mov_b32_e32 v49, v14
	v_mov_b32_e32 v56, v18
	v_mov_b32_e32 v57, v22
	v_mov_b32_e32 v60, v24
	v_mov_b32_e32 v61, v28
	v_mov_b32_e32 v68, v32
	v_mov_b32_e32 v69, v36
	v_pk_mul_f32 v[62:63], v[62:63], v[62:63]
	v_pk_mul_f32 v[70:71], v[70:71], v[70:71]
	v_pk_fma_f32 v[44:45], v[44:45], v[44:45], v[46:47]
	v_pk_fma_f32 v[46:47], v[52:53], v[52:53], v[54:55]
	v_mov_b32_e32 v50, v11
	v_mov_b32_e32 v51, v15
	v_mov_b32_e32 v58, v19
	v_mov_b32_e32 v59, v23
	v_mov_b32_e32 v64, v26
	v_mov_b32_e32 v65, v30
	v_mov_b32_e32 v72, v34
	v_mov_b32_e32 v73, v38
	v_pk_fma_f32 v[52:53], v[60:61], v[60:61], v[62:63]
	v_pk_fma_f32 v[54:55], v[68:69], v[68:69], v[70:71]
	v_pk_fma_f32 v[44:45], v[48:49], v[48:49], v[44:45]
	v_pk_fma_f32 v[46:47], v[56:57], v[56:57], v[46:47]
	v_mov_b32_e32 v66, v27
	v_mov_b32_e32 v67, v31
	v_mov_b32_e32 v74, v35
	v_mov_b32_e32 v75, v39
	v_pk_fma_f32 v[48:49], v[64:65], v[64:65], v[52:53]
	v_pk_fma_f32 v[52:53], v[72:73], v[72:73], v[54:55]
	v_pk_fma_f32 v[44:45], v[50:51], v[50:51], v[44:45]
	v_pk_fma_f32 v[46:47], v[58:59], v[58:59], v[46:47]
	v_pk_fma_f32 v[48:49], v[66:67], v[66:67], v[48:49]
	v_pk_fma_f32 v[50:51], v[74:75], v[74:75], v[52:53]
	v_mov_b32_e32 v52, v46
	v_mov_b32_e32 v53, v44
	v_mov_b32_e32 v44, v47
	v_mov_b32_e32 v46, v50
	v_mov_b32_e32 v47, v48
	v_pk_add_f32 v[44:45], v[52:53], v[44:45]
	v_mov_b32_e32 v48, v51
	v_pk_add_f32 v[44:45], v[44:45], v[46:47]
	s_nop 0
	v_pk_add_f32 v[44:45], v[44:45], v[48:49]
	ds_bpermute_b32 v47, v1, v45
	ds_bpermute_b32 v46, v1, v44
	s_waitcnt lgkmcnt(0)
	v_pk_add_f32 v[44:45], v[44:45], v[46:47]
	ds_bpermute_b32 v47, v3, v45
	ds_bpermute_b32 v46, v3, v44
	s_waitcnt lgkmcnt(0)
	v_pk_add_f32 v[44:45], v[44:45], v[46:47]
	ds_bpermute_b32 v47, v4, v45
	ds_bpermute_b32 v46, v4, v44
	s_waitcnt lgkmcnt(0)
	v_pk_add_f32 v[44:45], v[44:45], v[46:47]
	ds_bpermute_b32 v47, v5, v45
	ds_bpermute_b32 v46, v5, v44
	s_waitcnt lgkmcnt(0)
	v_pk_add_f32 v[44:45], v[44:45], v[46:47]
	ds_bpermute_b32 v47, v6, v45
	ds_bpermute_b32 v46, v6, v44
	s_waitcnt lgkmcnt(0)
	v_pk_add_f32 v[44:45], v[44:45], v[46:47]
	ds_bpermute_b32 v47, v7, v45
	ds_bpermute_b32 v46, v7, v44
	s_waitcnt lgkmcnt(0)
	v_pk_add_f32 v[44:45], v[44:45], v[46:47]
	s_nop 0
	v_pk_fma_f32 v[44:45], v[44:45], s[18:19], v[2:3] op_sel_hi:[1,0,0]
	s_nop 0
	v_mul_f32_e32 v46, 0x4b800000, v45
	v_cmp_gt_f32_e64 s[0:1], s4, v45
	v_mul_f32_e32 v47, 0x4b800000, v44
	v_cmp_gt_f32_e32 vcc, s4, v44
	v_cndmask_b32_e64 v45, v45, v46, s[0:1]
	v_rsq_f32_e32 v45, v45
	v_cndmask_b32_e32 v44, v44, v47, vcc
	v_rsq_f32_e32 v46, v44
	v_mul_f32_e32 v44, 0x45800000, v45
	v_cndmask_b32_e64 v44, v45, v44, s[0:1]
	v_mul_f32_e32 v47, 0x45800000, v46
	v_cndmask_b32_e32 v46, v46, v47, vcc
	v_pk_mul_f32 v[8:9], v[8:9], v[44:45] op_sel_hi:[1,0]
	v_pk_mul_f32 v[10:11], v[10:11], v[44:45] op_sel_hi:[1,0]
	v_pk_mul_f32 v[16:17], v[16:17], v[46:47] op_sel_hi:[1,0]
	v_pk_mul_f32 v[18:19], v[18:19], v[46:47] op_sel_hi:[1,0]
	v_pk_mul_f32 v[12:13], v[12:13], v[44:45] op_sel_hi:[1,0]
	v_pk_mul_f32 v[14:15], v[14:15], v[44:45] op_sel_hi:[1,0]
	v_pk_mul_f32 v[20:21], v[20:21], v[46:47] op_sel_hi:[1,0]
	v_pk_mul_f32 v[22:23], v[22:23], v[46:47] op_sel_hi:[1,0]
	v_pk_mul_f32 v[24:25], v[24:25], v[44:45] op_sel_hi:[1,0]
	v_pk_mul_f32 v[26:27], v[26:27], v[44:45] op_sel_hi:[1,0]
	v_pk_mul_f32 v[32:33], v[32:33], v[46:47] op_sel_hi:[1,0]
	v_pk_mul_f32 v[34:35], v[34:35], v[46:47] op_sel_hi:[1,0]
	v_pk_mul_f32 v[28:29], v[28:29], v[44:45] op_sel_hi:[1,0]
	v_pk_mul_f32 v[30:31], v[30:31], v[44:45] op_sel_hi:[1,0]
	v_pk_mul_f32 v[36:37], v[36:37], v[46:47] op_sel_hi:[1,0]
	v_pk_mul_f32 v[38:39], v[38:39], v[46:47] op_sel_hi:[1,0]
	v_cvt_pk_bf16_f32 v8, v8, v9
	v_cvt_pk_bf16_f32 v9, v10, v11
	v_cvt_pk_bf16_f32 v10, v16, v17
	v_cvt_pk_bf16_f32 v11, v18, v19
	v_cvt_pk_bf16_f32 v12, v12, v13
	v_cvt_pk_bf16_f32 v13, v14, v15
	v_cvt_pk_bf16_f32 v14, v20, v21
	v_cvt_pk_bf16_f32 v15, v22, v23
	v_cvt_pk_bf16_f32 v16, v24, v25
	v_cvt_pk_bf16_f32 v17, v26, v27
	v_cvt_pk_bf16_f32 v18, v32, v33
	v_cvt_pk_bf16_f32 v19, v34, v35
	v_cvt_pk_bf16_f32 v20, v28, v29
	v_cvt_pk_bf16_f32 v21, v30, v31
	v_cvt_pk_bf16_f32 v22, v36, v37
	v_cvt_pk_bf16_f32 v23, v38, v39
	global_store_dwordx2 v[40:41], v[8:9], off
	global_store_dwordx2 v[42:43], v[10:11], off
	global_store_dwordx2 v[40:41], v[12:13], off offset:512
	global_store_dwordx2 v[42:43], v[14:15], off offset:512
	global_store_dwordx2 v[40:41], v[16:17], off offset:1024
	global_store_dwordx2 v[42:43], v[18:19], off offset:1024
	global_store_dwordx2 v[40:41], v[20:21], off offset:1536
	global_store_dwordx2 v[42:43], v[22:23], off offset:1536
	s_cbranch_scc1 .LBB0_189
